# Hyena long-conv MFMA loops software-pipelined: next-block B fragment reads issued right behind the MFMA that consumed the register, next A fragment staged in spare registers
# baseline (speedup 1.0000x reference)
; __device__ __forceinline__ unsigned rev16(unsigned x) { return (x >> 16) | (x << 16); }
; __device__ __forceinline__ void hy_conv(const bf16_t* Gf0, const bf16_t* Gf1, const bf16_t* Ur, f32x16 (&acc)[4], int w, int lane) {
;     const int i = lane & 31, h = lane >> 5, bb = (lane >> 2) & 7, jj = lane & 3;
;     const int T0 = 96 + 512 * w;
; #pragma unroll
;     for (int mm = 0; mm < 4; ++mm)
; #pragma unroll
;         for (int r = 0; r < 16; ++r) acc[mm][r] = 0.f;
;     const int P0 = GOFF + (T0 - 4192) + i - 8 * h - 7;
;     const bf16_t* gp = ((P0 & 1) ? Gf1 : Gf0) + (P0 & ~1);
;     const bf16_t* up = Ur + bb * UP + (URO - 7 - 8 * h + 32 * jj - 4192);
;     int nit = 287; asm volatile("" : "+s"(nit));
;     union AF { bf16x8 v; unsigned u[4]; };
;     AF ac; bf16x8 bc[4];
;     { const unsigned* g4 = (const unsigned*)gp; ac.u[0] = g4[0]; ac.u[1] = g4[1]; ac.u[2] = g4[2]; ac.u[3] = g4[3];
; #pragma unroll
;       for (int mm = 0; mm < 4; ++mm) bc[mm] = *(const bf16x8*)(up - 128 * mm); }
; #pragma unroll 2
;     for (int it = 0; it < nit; ++it) {
;         const int itn = (it + 1 < nit) ? it + 1 : it;
;         AF an; bf16x8 bn[4];
;         { const unsigned* g4 = (const unsigned*)(gp + 16 * itn); an.u[0] = g4[0]; an.u[1] = g4[1]; an.u[2] = g4[2]; an.u[3] = g4[3];
; #pragma unroll
;           for (int mm = 0; mm < 4; ++mm) bn[mm] = *(const bf16x8*)(up + 16 * itn - 128 * mm); }
; #pragma unroll
;         for (int mm = 0; mm < 4; ++mm) acc[mm] = __builtin_amdgcn_mfma_f32_32x32x16_bf16(ac.v, bc[mm], acc[mm], 0, 0, 0);
;         ac = an;
; #pragma unroll
;         for (int mm = 0; mm < 4; ++mm) bc[mm] = bn[mm];
;     }
; __device__ __forceinline__ void hy_conv_item(const Ctx& C, int l, int c) {
;     ...
;     {
;         u32x4 vin[8];
; #pragma unroll
;         for (int k = 0; k < 8; ++k) { const int id = tid + NTHR * k, bb_ = id >> 9, off = (id & 511) * 8; vin[k] = *(const u32x4*)(vsrc + (size_t)bb_ * SEQ + off); }
; #pragma unroll
;         for (int k = 0; k < 8; ++k) { const int id = tid + NTHR * k, bb_ = id >> 9, off = (id & 511) * 8;
;             u32x4 o; o.x = rev16(vin[k].w); o.y = rev16(vin[k].z); o.z = rev16(vin[k].y); o.w = rev16(vin[k].x);
;             *(u32x4*)(U + bb_ * UP + (URO - 7 - off)) = o; }
;     }
.LBB0_632:
	s_or_b64 exec, exec, s[0:1]
	s_lshl_b64 s[0:1], s[6:7], 16
	v_lshl_add_u64 v[28:29], v[88:89], 0, s[0:1]
	v_lshl_add_u64 v[0:1], v[28:29], 0, v[90:91]
	s_waitcnt lgkmcnt(0)
	s_barrier
	global_load_dwordx4 v[0:3], v[0:1], off
	v_lshl_add_u64 v[4:5], v[28:29], 0, v[92:93]
	v_lshl_add_u64 v[8:9], v[28:29], 0, v[94:95]
	v_lshl_add_u64 v[12:13], v[28:29], 0, v[96:97]
	v_lshl_add_u64 v[16:17], v[28:29], 0, v[98:99]
	v_lshl_add_u64 v[20:21], v[28:29], 0, v[100:101]
	v_lshl_add_u64 v[24:25], v[28:29], 0, v[102:103]
	v_lshl_add_u64 v[28:29], v[28:29], 0, v[104:105]
	global_load_dwordx4 v[4:7], v[4:5], off
	s_movk_i32 s0, 0x11f
	global_load_dwordx4 v[8:11], v[8:9], off
	s_mov_b32 s66, 0x358637bd
	global_load_dwordx4 v[12:15], v[12:13], off
	s_waitcnt vmcnt(3)
	v_alignbit_b32 v32, v3, v3, 16
	global_load_dwordx4 v[16:19], v[16:17], off
	v_alignbit_b32 v33, v2, v2, 16
	global_load_dwordx4 v[20:23], v[20:21], off
	v_alignbit_b32 v34, v1, v1, 16
	global_load_dwordx4 v[24:27], v[24:25], off
	v_alignbit_b32 v35, v0, v0, 16
	global_load_dwordx4 v[28:31], v[28:29], off
	s_waitcnt vmcnt(6)
	v_alignbit_b32 v0, v7, v7, 16
	v_alignbit_b32 v1, v6, v6, 16
	v_alignbit_b32 v2, v5, v5, 16
	v_alignbit_b32 v3, v4, v4, 16
	s_waitcnt vmcnt(5)
	v_alignbit_b32 v4, v11, v11, 16
	v_alignbit_b32 v5, v10, v10, 16
	v_alignbit_b32 v6, v9, v9, 16
	v_alignbit_b32 v7, v8, v8, 16
	s_waitcnt vmcnt(4)
	v_alignbit_b32 v8, v15, v15, 16
	v_alignbit_b32 v9, v14, v14, 16
	v_alignbit_b32 v10, v13, v13, 16
	v_alignbit_b32 v11, v12, v12, 16
	s_waitcnt vmcnt(3)
	v_alignbit_b32 v12, v19, v19, 16
	v_alignbit_b32 v13, v18, v18, 16
	v_alignbit_b32 v14, v17, v17, 16
	v_alignbit_b32 v15, v16, v16, 16
	s_waitcnt vmcnt(2)
	v_alignbit_b32 v16, v23, v23, 16
	v_alignbit_b32 v17, v22, v22, 16
	v_alignbit_b32 v18, v21, v21, 16
	v_alignbit_b32 v19, v20, v20, 16
	s_waitcnt vmcnt(1)
	v_alignbit_b32 v20, v27, v27, 16
	v_alignbit_b32 v21, v26, v26, 16
	v_alignbit_b32 v22, v25, v25, 16
	v_alignbit_b32 v23, v24, v24, 16
	s_waitcnt vmcnt(0)
	v_alignbit_b32 v24, v31, v31, 16
	v_alignbit_b32 v25, v30, v30, 16
	v_alignbit_b32 v26, v29, v29, 16
	v_alignbit_b32 v27, v28, v28, 16
	ds_write_b128 v118, v[32:35]
	ds_write_b128 v119, v[0:3]
	ds_write_b128 v120, v[4:7]
	ds_write_b128 v121, v[8:11]
	ds_write_b128 v122, v[12:15]
	ds_write_b128 v123, v[16:19]
	ds_write_b128 v124, v[20:23]
	ds_write_b128 v125, v[24:27]
	s_waitcnt lgkmcnt(0)
	s_barrier
	s_cmp_gt_i32 s0, 0
	s_cbranch_scc0 .LBB0_635
	ds_read2_b32 v[70:71], v126 offset1:1
	ds_read2_b32 v[72:73], v126 offset0:2 offset1:3
	ds_read_b128 v[82:85], v127 offset:800
	ds_read_b128 v[78:81], v127 offset:544
	ds_read_b128 v[74:77], v127 offset:288
	ds_read_b128 v[66:69], v127 offset:32
	v_mov_b32_e32 v0, 0
	s_mov_b32 s1, 0
	v_mov_b32_e32 v1, v0
	v_mov_b32_e32 v2, v0
	v_mov_b32_e32 v3, v0
	v_mov_b32_e32 v4, v0
	v_mov_b32_e32 v5, v0
	v_mov_b32_e32 v6, v0
	v_mov_b32_e32 v7, v0
	v_mov_b32_e32 v8, v0
	v_mov_b32_e32 v9, v0
	v_mov_b32_e32 v10, v0
	v_mov_b32_e32 v11, v0
	v_mov_b32_e32 v12, v0
	v_mov_b32_e32 v13, v0
	v_mov_b32_e32 v14, v0
	v_mov_b32_e32 v15, v0
	v_mov_b32_e32 v16, v0
	v_mov_b32_e32 v17, v0
	v_mov_b32_e32 v18, v0
	v_mov_b32_e32 v19, v0
	v_mov_b32_e32 v20, v0
	v_mov_b32_e32 v21, v0
	v_mov_b32_e32 v22, v0
	v_mov_b32_e32 v23, v0
	v_mov_b32_e32 v24, v0
	v_mov_b32_e32 v25, v0
	v_mov_b32_e32 v26, v0
	v_mov_b32_e32 v27, v0
	v_mov_b32_e32 v28, v0
	v_mov_b32_e32 v29, v0
	v_mov_b32_e32 v30, v0
	v_mov_b32_e32 v31, v0
	v_mov_b32_e32 v48, v0
	v_mov_b32_e32 v49, v0
	v_mov_b32_e32 v50, v0
	v_mov_b32_e32 v51, v0
	v_mov_b32_e32 v52, v0
	v_mov_b32_e32 v53, v0
	v_mov_b32_e32 v54, v0
	v_mov_b32_e32 v55, v0
	v_mov_b32_e32 v56, v0
	v_mov_b32_e32 v57, v0
	v_mov_b32_e32 v58, v0
	v_mov_b32_e32 v59, v0
	v_mov_b32_e32 v60, v0
	v_mov_b32_e32 v61, v0
	v_mov_b32_e32 v62, v0
	v_mov_b32_e32 v63, v0
	v_mov_b32_e32 v32, v0
	v_mov_b32_e32 v33, v0
	v_mov_b32_e32 v34, v0
	v_mov_b32_e32 v35, v0
	v_mov_b32_e32 v36, v0
	v_mov_b32_e32 v37, v0
	v_mov_b32_e32 v38, v0
	v_mov_b32_e32 v39, v0
	v_mov_b32_e32 v40, v0
	v_mov_b32_e32 v41, v0
	v_mov_b32_e32 v42, v0
	v_mov_b32_e32 v43, v0
	v_mov_b32_e32 v44, v0
	v_mov_b32_e32 v45, v0
	v_mov_b32_e32 v46, v0
	v_mov_b32_e32 v47, v0
	s_waitcnt lgkmcnt(0)
.LBB0_634:
	s_add_i32 s8, s1, 1
	s_cmp_lt_i32 s8, s0
	s_cselect_b32 s9, s8, s1
	s_lshl_b32 s9, s9, 5
	v_add_u32_e32 v154, s9, v127
	v_add_u32_e32 v155, s9, v126
	s_mov_b32 s1, s8
	s_cmp_lg_u32 s0, s8
	s_waitcnt lgkmcnt(3)
	v_mfma_f32_32x32x16_bf16 v[48:63], v[70:73], v[82:85], v[48:63]
	ds_read2_b32 v[150:151], v155 offset1:1
	ds_read2_b32 v[152:153], v155 offset0:2 offset1:3
	ds_read_b128 v[82:85], v154 offset:800
	s_waitcnt lgkmcnt(5)
	v_mfma_f32_32x32x16_bf16 v[32:47], v[70:73], v[78:81], v[32:47]
	ds_read_b128 v[78:81], v154 offset:544
	s_waitcnt lgkmcnt(5)
	v_mfma_f32_32x32x16_bf16 v[16:31], v[70:73], v[74:77], v[16:31]
	ds_read_b128 v[74:77], v154 offset:288
	s_waitcnt lgkmcnt(5)
	v_mfma_f32_32x32x16_bf16 v[0:15], v[70:73], v[66:69], v[0:15]
	s_waitcnt lgkmcnt(3)
	v_mov_b32_e32 v70, v150
	v_mov_b32_e32 v71, v151
	v_mov_b32_e32 v72, v152
	v_mov_b32_e32 v73, v153
	ds_read_b128 v[66:69], v154 offset:32
	s_cbranch_scc1 .LBB0_634
	s_waitcnt lgkmcnt(0)
	s_branch .LBB0_636

; __device__ __forceinline__ unsigned cvt_pk_bf16(float lo, float hi) { f32x2_t v = {lo, hi}; bf2_t r = __builtin_convertvector(v, bf2_t); return __builtin_bit_cast(unsigned, r); }
; __device__ __forceinline__ float bflo(unsigned u) { return __uint_as_float(u << 16); }
; __device__ __forceinline__ float bfhi(unsigned u) { return __uint_as_float(u & 0xffff0000u); }
; __device__ __forceinline__ void hy_conv_item(const Ctx& C, int l, int c) {
;     ...
;     __syncthreads();
;     u32x2 xall[4][4];
; #pragma unroll
;     for (int mm = 0; mm < 4; ++mm)
; #pragma unroll
;         for (int k4 = 0; k4 < 4; ++k4) { const int t = 96 + 512 * w + 128 * mm - 32 * jj + 8 * k4 + 4 * h; xall[mm][k4] = *(const u32x2*)(x1src + (size_t)bb * SEQ + t); }
; #pragma unroll
;     for (int mm = 0; mm < 4; ++mm)
; #pragma unroll
;         for (int k4 = 0; k4 < 4; ++k4) { const int t = 96 + 512 * w + 128 * mm - 32 * jj + 8 * k4 + 4 * h;
;             const u32x2 xv = xall[mm][k4];
;             u32x2 o; o.x = cvt_pk_bf16(acc[mm][4 * k4 + 3] * bfhi(xv.y), acc[mm][4 * k4 + 2] * bflo(xv.y)); o.y = cvt_pk_bf16(acc[mm][4 * k4 + 1] * bfhi(xv.x), acc[mm][4 * k4] * bflo(xv.x));
;             *(u32x2*)(U + bb * UP + (URO - 3 - t)) = o; }
.LBB0_636:
	s_lshl_b64 s[8:9], s[6:7], 16
	s_waitcnt lgkmcnt(4)
	v_lshl_add_u64 v[66:67], v[106:107], 0, s[8:9]
	s_mov_b64 s[8:9], 0x1000000
	v_lshl_add_u64 v[66:67], v[66:67], 0, s[8:9]
	s_waitcnt lgkmcnt(0)
	s_barrier
	global_load_dwordx2 v[142:143], v[66:67], off offset:192
	global_load_dwordx2 v[144:145], v[66:67], off offset:208
	global_load_dwordx2 v[146:147], v[66:67], off offset:224
	global_load_dwordx2 v[148:149], v[66:67], off offset:240
	global_load_dwordx2 v[112:113], v[66:67], off offset:448
	global_load_dwordx2 v[110:111], v[66:67], off offset:464
	global_load_dwordx2 v[84:85], v[66:67], off offset:480
	global_load_dwordx2 v[82:83], v[66:67], off offset:496
	global_load_dwordx2 v[80:81], v[66:67], off offset:704
	global_load_dwordx2 v[78:79], v[66:67], off offset:720
	global_load_dwordx2 v[76:77], v[66:67], off offset:736
	global_load_dwordx2 v[74:75], v[66:67], off offset:752
	global_load_dwordx2 v[72:73], v[66:67], off offset:960
	global_load_dwordx2 v[70:71], v[66:67], off offset:976
	global_load_dwordx2 v[68:69], v[66:67], off offset:992
	s_nop 0
	global_load_dwordx2 v[66:67], v[66:67], off offset:1008
	v_mov_b32_e32 v152, v51
	v_mov_b32_e32 v153, v50
	s_lshl_b64 s[0:1], s[6:7], 15
	s_movk_i32 s8, 0x11f
	s_waitcnt vmcnt(15)
	v_and_b32_e32 v150, 0xffff0000, v143
	v_lshlrev_b32_e32 v151, 16, v143
	v_pk_mul_f32 v[50:51], v[152:153], v[150:151]
	v_and_b32_e32 v150, 0xffff0000, v142
	v_lshlrev_b32_e32 v151, 16, v142
	v_mov_b32_e32 v142, v49
	v_mov_b32_e32 v143, v48
	v_pk_mul_f32 v[48:49], v[142:143], v[150:151]
	v_cvt_pk_bf16_f32 v50, v50, v51
	v_cvt_pk_bf16_f32 v51, v48, v49
	s_waitcnt vmcnt(14)
	v_and_b32_e32 v48, 0xffff0000, v145
	v_lshlrev_b32_e32 v49, 16, v145
	v_mov_b32_e32 v142, v55
	v_mov_b32_e32 v143, v54
	v_pk_mul_f32 v[48:49], v[142:143], v[48:49]
	v_mov_b32_e32 v142, v53
	v_cvt_pk_bf16_f32 v54, v48, v49
	v_and_b32_e32 v48, 0xffff0000, v144
	v_lshlrev_b32_e32 v49, 16, v144
	v_mov_b32_e32 v143, v52
	v_pk_mul_f32 v[48:49], v[142:143], v[48:49]
	v_mov_b32_e32 v52, v59
	v_cvt_pk_bf16_f32 v55, v48, v49
	v_add_u32_e32 v48, 0x2000, v128
	ds_write2_b64 v48, v[54:55], v[50:51] offset0:99 offset1:101
	s_waitcnt vmcnt(13)
	v_and_b32_e32 v50, 0xffff0000, v147
	v_lshlrev_b32_e32 v51, 16, v147
	v_mov_b32_e32 v53, v58
	v_pk_mul_f32 v[50:51], v[52:53], v[50:51]
	v_and_b32_e32 v52, 0xffff0000, v146
	v_lshlrev_b32_e32 v53, 16, v146
	v_mov_b32_e32 v54, v57
	v_mov_b32_e32 v55, v56
	v_pk_mul_f32 v[52:53], v[54:55], v[52:53]
	v_cvt_pk_bf16_f32 v50, v50, v51
	v_cvt_pk_bf16_f32 v51, v52, v53
	s_waitcnt vmcnt(12)
	v_and_b32_e32 v52, 0xffff0000, v149
	v_lshlrev_b32_e32 v53, 16, v149
	v_mov_b32_e32 v54, v63
	v_mov_b32_e32 v55, v62
	v_pk_mul_f32 v[52:53], v[54:55], v[52:53]
	v_and_b32_e32 v54, 0xffff0000, v148
	v_lshlrev_b32_e32 v55, 16, v148
	v_mov_b32_e32 v56, v61
	v_mov_b32_e32 v57, v60
	v_pk_mul_f32 v[54:55], v[56:57], v[54:55]
	v_cvt_pk_bf16_f32 v52, v52, v53
	v_cvt_pk_bf16_f32 v53, v54, v55
	ds_write2_b64 v48, v[52:53], v[50:51] offset0:95 offset1:97
	s_waitcnt vmcnt(11)
	v_and_b32_e32 v50, 0xffff0000, v113
	v_lshlrev_b32_e32 v51, 16, v113
	v_mov_b32_e32 v52, v35
	v_mov_b32_e32 v53, v34
	v_pk_mul_f32 v[34:35], v[52:53], v[50:51]
	v_and_b32_e32 v50, 0xffff0000, v112
	v_lshlrev_b32_e32 v51, 16, v112
	v_mov_b32_e32 v52, v33
	v_mov_b32_e32 v53, v32
	v_pk_mul_f32 v[32:33], v[52:53], v[50:51]
	v_cvt_pk_bf16_f32 v34, v34, v35
	v_cvt_pk_bf16_f32 v35, v32, v33
	s_waitcnt vmcnt(10)
	v_and_b32_e32 v32, 0xffff0000, v111
	v_lshlrev_b32_e32 v33, 16, v111
	v_mov_b32_e32 v50, v39
	v_mov_b32_e32 v51, v38
	v_pk_mul_f32 v[32:33], v[50:51], v[32:33]
	v_and_b32_e32 v38, 0xffff0000, v110
	v_lshlrev_b32_e32 v39, 16, v110
	v_mov_b32_e32 v50, v37
	v_mov_b32_e32 v51, v36
	v_pk_mul_f32 v[36:37], v[50:51], v[38:39]
	v_cvt_pk_bf16_f32 v32, v32, v33
	v_cvt_pk_bf16_f32 v33, v36, v37
	ds_write2_b64 v48, v[32:33], v[34:35] offset0:67 offset1:69
	s_waitcnt vmcnt(9)
	v_and_b32_e32 v32, 0xffff0000, v85
	v_lshlrev_b32_e32 v33, 16, v85
	v_mov_b32_e32 v34, v43
	v_mov_b32_e32 v35, v42
	v_pk_mul_f32 v[32:33], v[34:35], v[32:33]
	v_and_b32_e32 v34, 0xffff0000, v84
	v_lshlrev_b32_e32 v35, 16, v84
	v_mov_b32_e32 v36, v41
	v_mov_b32_e32 v37, v40
	v_pk_mul_f32 v[34:35], v[36:37], v[34:35]
	v_cvt_pk_bf16_f32 v32, v32, v33
	v_cvt_pk_bf16_f32 v33, v34, v35
	s_waitcnt vmcnt(8)
	v_and_b32_e32 v34, 0xffff0000, v83
	v_lshlrev_b32_e32 v35, 16, v83
	v_mov_b32_e32 v36, v47
	v_mov_b32_e32 v37, v46
	v_pk_mul_f32 v[34:35], v[36:37], v[34:35]
	v_and_b32_e32 v36, 0xffff0000, v82
	v_lshlrev_b32_e32 v37, 16, v82
	v_mov_b32_e32 v38, v45
	v_mov_b32_e32 v39, v44
	v_pk_mul_f32 v[36:37], v[38:39], v[36:37]
	v_cvt_pk_bf16_f32 v34, v34, v35
	v_cvt_pk_bf16_f32 v35, v36, v37
	ds_write2_b64 v48, v[34:35], v[32:33] offset0:63 offset1:65
	s_waitcnt vmcnt(7)
	v_and_b32_e32 v32, 0xffff0000, v81
	v_lshlrev_b32_e32 v33, 16, v81
	v_mov_b32_e32 v34, v19
	v_mov_b32_e32 v35, v18
	v_pk_mul_f32 v[18:19], v[34:35], v[32:33]
	v_and_b32_e32 v32, 0xffff0000, v80
	v_lshlrev_b32_e32 v33, 16, v80
	v_mov_b32_e32 v34, v17
	v_mov_b32_e32 v35, v16
	v_pk_mul_f32 v[16:17], v[34:35], v[32:33]
	v_cvt_pk_bf16_f32 v18, v18, v19
	v_cvt_pk_bf16_f32 v19, v16, v17
	s_waitcnt vmcnt(6)
	v_and_b32_e32 v16, 0xffff0000, v79
	v_lshlrev_b32_e32 v17, 16, v79
	v_mov_b32_e32 v32, v23
	v_mov_b32_e32 v33, v22
	v_pk_mul_f32 v[16:17], v[32:33], v[16:17]
	v_and_b32_e32 v22, 0xffff0000, v78
	v_lshlrev_b32_e32 v23, 16, v78
	v_mov_b32_e32 v32, v21
	v_mov_b32_e32 v33, v20
	v_pk_mul_f32 v[20:21], v[32:33], v[22:23]
	v_cvt_pk_bf16_f32 v16, v16, v17
	v_cvt_pk_bf16_f32 v17, v20, v21
	ds_write2_b64 v48, v[16:17], v[18:19] offset0:35 offset1:37
	s_waitcnt vmcnt(5)
; __device__ __forceinline__ unsigned cvt_pk_bf16(float lo, float hi) { f32x2_t v = {lo, hi}; bf2_t r = __builtin_convertvector(v, bf2_t); return __builtin_bit_cast(unsigned, r); }
; __device__ __forceinline__ void hy_conv(const bf16_t* Gf0, const bf16_t* Gf1, const bf16_t* Ur, f32x16 (&acc)[4], int w, int lane) {
;     const int i = lane & 31, h = lane >> 5, bb = (lane >> 2) & 7, jj = lane & 3;
;     const int T0 = 96 + 512 * w;
; #pragma unroll
;     for (int mm = 0; mm < 4; ++mm)
; #pragma unroll
;         for (int r = 0; r < 16; ++r) acc[mm][r] = 0.f;
;     const int P0 = GOFF + (T0 - 4192) + i - 8 * h - 7;
;     const bf16_t* gp = ((P0 & 1) ? Gf1 : Gf0) + (P0 & ~1);
;     const bf16_t* up = Ur + bb * UP + (URO - 7 - 8 * h + 32 * jj - 4192);
;     int nit = 287; asm volatile("" : "+s"(nit));
;     union AF { bf16x8 v; unsigned u[4]; };
;     AF ac; bf16x8 bc[4];
;     { const unsigned* g4 = (const unsigned*)gp; ac.u[0] = g4[0]; ac.u[1] = g4[1]; ac.u[2] = g4[2]; ac.u[3] = g4[3];
; #pragma unroll
;       for (int mm = 0; mm < 4; ++mm) bc[mm] = *(const bf16x8*)(up - 128 * mm); }
; #pragma unroll 2
;     for (int it = 0; it < nit; ++it) {
;         const int itn = (it + 1 < nit) ? it + 1 : it;
;         AF an; bf16x8 bn[4];
;         { const unsigned* g4 = (const unsigned*)(gp + 16 * itn); an.u[0] = g4[0]; an.u[1] = g4[1]; an.u[2] = g4[2]; an.u[3] = g4[3];
; #pragma unroll
;           for (int mm = 0; mm < 4; ++mm) bn[mm] = *(const bf16x8*)(up + 16 * itn - 128 * mm); }
; #pragma unroll
;         for (int mm = 0; mm < 4; ++mm) acc[mm] = __builtin_amdgcn_mfma_f32_32x32x16_bf16(ac.v, bc[mm], acc[mm], 0, 0, 0);
;         ac = an;
; #pragma unroll
;         for (int mm = 0; mm < 4; ++mm) bc[mm] = bn[mm];
;     }
; __device__ __forceinline__ void hy_conv_item(const Ctx& C, int l, int c) {
;     ...
;     for (int mm = 0; mm < 4; ++mm)
; #pragma unroll
;         for (int k4 = 0; k4 < 4; ++k4) { const int t = 96 + 512 * w + 128 * mm - 32 * jj + 8 * k4 + 4 * h;
;             const u32x2 xv = xall[mm][k4];
;             u32x2 o; o.x = cvt_pk_bf16(acc[mm][4 * k4 + 3] * bfhi(xv.y), acc[mm][4 * k4 + 2] * bflo(xv.y)); o.y = cvt_pk_bf16(acc[mm][4 * k4 + 1] * bfhi(xv.x), acc[mm][4 * k4] * bflo(xv.x));
;             *(u32x2*)(U + bb * UP + (URO - 3 - t)) = o; }
;     __syncthreads();
;     hy_conv(G20, G21, U, acc, w, lane);
	v_and_b32_e32 v16, 0xffff0000, v77
	v_lshlrev_b32_e32 v17, 16, v77
	v_mov_b32_e32 v18, v27
	v_mov_b32_e32 v19, v26
	v_pk_mul_f32 v[16:17], v[18:19], v[16:17]
	v_and_b32_e32 v18, 0xffff0000, v76
	v_lshlrev_b32_e32 v19, 16, v76
	v_mov_b32_e32 v20, v25
	v_mov_b32_e32 v21, v24
	v_pk_mul_f32 v[18:19], v[20:21], v[18:19]
	v_cvt_pk_bf16_f32 v16, v16, v17
	v_cvt_pk_bf16_f32 v17, v18, v19
	s_waitcnt vmcnt(4)
	v_and_b32_e32 v18, 0xffff0000, v75
	v_lshlrev_b32_e32 v19, 16, v75
	v_mov_b32_e32 v20, v31
	v_mov_b32_e32 v21, v30
	v_pk_mul_f32 v[18:19], v[20:21], v[18:19]
	v_and_b32_e32 v20, 0xffff0000, v74
	v_lshlrev_b32_e32 v21, 16, v74
	v_mov_b32_e32 v22, v29
	v_mov_b32_e32 v23, v28
	v_pk_mul_f32 v[20:21], v[22:23], v[20:21]
	v_cvt_pk_bf16_f32 v18, v18, v19
	v_cvt_pk_bf16_f32 v19, v20, v21
	ds_write2_b64 v48, v[18:19], v[16:17] offset0:31 offset1:33
	s_waitcnt vmcnt(3)
	v_and_b32_e32 v16, 0xffff0000, v73
	v_lshlrev_b32_e32 v17, 16, v73
	v_mov_b32_e32 v18, v3
	v_mov_b32_e32 v19, v2
	v_pk_mul_f32 v[2:3], v[18:19], v[16:17]
	v_and_b32_e32 v16, 0xffff0000, v72
	v_lshlrev_b32_e32 v17, 16, v72
	v_mov_b32_e32 v18, v1
	v_mov_b32_e32 v19, v0
	v_pk_mul_f32 v[0:1], v[18:19], v[16:17]
	v_cvt_pk_bf16_f32 v2, v2, v3
	v_cvt_pk_bf16_f32 v3, v0, v1
	s_waitcnt vmcnt(2)
	v_and_b32_e32 v0, 0xffff0000, v71
	v_lshlrev_b32_e32 v1, 16, v71
	v_mov_b32_e32 v16, v7
	v_mov_b32_e32 v17, v6
	v_pk_mul_f32 v[0:1], v[16:17], v[0:1]
	v_and_b32_e32 v6, 0xffff0000, v70
	v_lshlrev_b32_e32 v7, 16, v70
	v_mov_b32_e32 v16, v5
	v_mov_b32_e32 v17, v4
	v_pk_mul_f32 v[4:5], v[16:17], v[6:7]
	v_cvt_pk_bf16_f32 v0, v0, v1
	v_cvt_pk_bf16_f32 v1, v4, v5
	ds_write2_b64 v48, v[0:1], v[2:3] offset0:3 offset1:5
	s_waitcnt vmcnt(1)
	v_and_b32_e32 v0, 0xffff0000, v69
	v_lshlrev_b32_e32 v1, 16, v69
	v_mov_b32_e32 v2, v11
	v_mov_b32_e32 v3, v10
	v_pk_mul_f32 v[0:1], v[2:3], v[0:1]
	v_and_b32_e32 v2, 0xffff0000, v68
	v_lshlrev_b32_e32 v3, 16, v68
	v_mov_b32_e32 v4, v9
	v_mov_b32_e32 v5, v8
	v_pk_mul_f32 v[2:3], v[4:5], v[2:3]
	v_cvt_pk_bf16_f32 v0, v0, v1
	v_cvt_pk_bf16_f32 v1, v2, v3
	s_waitcnt vmcnt(0)
	v_and_b32_e32 v2, 0xffff0000, v67
	v_lshlrev_b32_e32 v3, 16, v67
	v_mov_b32_e32 v4, v15
	v_mov_b32_e32 v5, v14
	v_pk_mul_f32 v[2:3], v[4:5], v[2:3]
	v_and_b32_e32 v4, 0xffff0000, v66
	v_lshlrev_b32_e32 v5, 16, v66
	v_mov_b32_e32 v6, v13
	v_mov_b32_e32 v7, v12
	v_pk_mul_f32 v[4:5], v[6:7], v[4:5]
	v_cvt_pk_bf16_f32 v2, v2, v3
	v_cvt_pk_bf16_f32 v3, v4, v5
	v_add_u32_e32 v4, 0x1c00, v128
	ds_write2_b64 v4, v[2:3], v[0:1] offset0:127 offset1:129
	s_waitcnt lgkmcnt(0)
	s_barrier
	s_cmp_lt_i32 s8, 1
	s_cbranch_scc1 .LBB0_604
	ds_read2_b32 v[70:71], v129 offset1:1
	ds_read2_b32 v[72:73], v129 offset0:2 offset1:3
	ds_read_b128 v[82:85], v127 offset:800
	ds_read_b128 v[78:81], v127 offset:544
	ds_read_b128 v[74:77], v127 offset:288
	ds_read_b128 v[66:69], v127 offset:32
	v_mov_b32_e32 v0, 0
	s_mov_b32 s9, 0
	v_mov_b32_e32 v1, v0
	v_mov_b32_e32 v2, v0
	v_mov_b32_e32 v3, v0
	v_mov_b32_e32 v4, v0
	v_mov_b32_e32 v5, v0
	v_mov_b32_e32 v6, v0
	v_mov_b32_e32 v7, v0
	v_mov_b32_e32 v8, v0
	v_mov_b32_e32 v9, v0
	v_mov_b32_e32 v10, v0
	v_mov_b32_e32 v11, v0
	v_mov_b32_e32 v12, v0
	v_mov_b32_e32 v13, v0
	v_mov_b32_e32 v14, v0
	v_mov_b32_e32 v15, v0
	v_mov_b32_e32 v16, v0
	v_mov_b32_e32 v17, v0
	v_mov_b32_e32 v18, v0
	v_mov_b32_e32 v19, v0
	v_mov_b32_e32 v20, v0
	v_mov_b32_e32 v21, v0
	v_mov_b32_e32 v22, v0
	v_mov_b32_e32 v23, v0
	v_mov_b32_e32 v24, v0
	v_mov_b32_e32 v25, v0
	v_mov_b32_e32 v26, v0
	v_mov_b32_e32 v27, v0
	v_mov_b32_e32 v28, v0
	v_mov_b32_e32 v29, v0
	v_mov_b32_e32 v30, v0
	v_mov_b32_e32 v31, v0
	v_mov_b32_e32 v48, v0
	v_mov_b32_e32 v49, v0
	v_mov_b32_e32 v50, v0
	v_mov_b32_e32 v51, v0
	v_mov_b32_e32 v52, v0
	v_mov_b32_e32 v53, v0
	v_mov_b32_e32 v54, v0
	v_mov_b32_e32 v55, v0
	v_mov_b32_e32 v56, v0
	v_mov_b32_e32 v57, v0
	v_mov_b32_e32 v58, v0
	v_mov_b32_e32 v59, v0
	v_mov_b32_e32 v60, v0
	v_mov_b32_e32 v61, v0
	v_mov_b32_e32 v62, v0
	v_mov_b32_e32 v63, v0
	v_mov_b32_e32 v32, v0
	v_mov_b32_e32 v33, v0
	v_mov_b32_e32 v34, v0
	v_mov_b32_e32 v35, v0
	v_mov_b32_e32 v36, v0
	v_mov_b32_e32 v37, v0
	v_mov_b32_e32 v38, v0
	v_mov_b32_e32 v39, v0
	v_mov_b32_e32 v40, v0
	v_mov_b32_e32 v41, v0
	v_mov_b32_e32 v42, v0
	v_mov_b32_e32 v43, v0
	v_mov_b32_e32 v44, v0
	v_mov_b32_e32 v45, v0
	v_mov_b32_e32 v46, v0
	v_mov_b32_e32 v47, v0
	s_waitcnt lgkmcnt(0)
.LBB0_638:
	s_add_i32 s10, s9, 1
	s_cmp_lt_i32 s10, s8
	s_cselect_b32 s11, s10, s9
	s_lshl_b32 s11, s11, 5
	v_add_u32_e32 v154, s11, v127
	v_add_u32_e32 v155, s11, v129
	s_mov_b32 s9, s10
	s_cmp_lg_u32 s8, s10
	s_waitcnt lgkmcnt(3)
	v_mfma_f32_32x32x16_bf16 v[48:63], v[70:73], v[82:85], v[48:63]
	ds_read2_b32 v[150:151], v155 offset1:1
	ds_read2_b32 v[152:153], v155 offset0:2 offset1:3
	ds_read_b128 v[82:85], v154 offset:800
	s_waitcnt lgkmcnt(5)
	v_mfma_f32_32x32x16_bf16 v[32:47], v[70:73], v[78:81], v[32:47]
	ds_read_b128 v[78:81], v154 offset:544
	s_waitcnt lgkmcnt(5)
	v_mfma_f32_32x32x16_bf16 v[16:31], v[70:73], v[74:77], v[16:31]
	ds_read_b128 v[74:77], v154 offset:288
	s_waitcnt lgkmcnt(5)
	v_mfma_f32_32x32x16_bf16 v[0:15], v[70:73], v[66:69], v[0:15]
	s_waitcnt lgkmcnt(3)
	v_mov_b32_e32 v70, v150
	v_mov_b32_e32 v71, v151
	v_mov_b32_e32 v72, v152
	v_mov_b32_e32 v73, v153
	ds_read_b128 v[66:69], v154 offset:32
	s_cbranch_scc1 .LBB0_638
	s_waitcnt lgkmcnt(0)
	s_branch .LBB0_605
